# in-proj K-loop header: compiler's vmcnt(0) (WAW cover for already-waited epilogue loads) relaxed to vmcnt(6) so the 6 LDS-DMA stages the 8-phase template keeps in flight stay in flight across the back
# speedup vs baseline: 1.0126x; 1.0114x over previous
; #define PG_STAGE(bufoff, gbase, voff) do { _Pragma("unroll") for (int _i = 0; _i < 2; ++_i) \
;     __builtin_amdgcn_global_load_lds((const unsigned*)((const char*)(gbase) + (voff)[_i]), (PG_LAS unsigned*)(lds + (bufoff) + ldsw + _i * 8192), 16, 0, 0); } while (0)
; #define PG_LDA(dst, b, h) do { _Pragma("unroll") for (int m = 0; m < 4; ++m) _Pragma("unroll") for (int k = 0; k < 2; ++k) dst[m][k] = *(const PG_LAS bf16x8*)(lds + PG_SA(b, h) + aoff + m * 2048 + k * 1024); } while (0)
; #define PG_LDB(dst, b, h) do { _Pragma("unroll") for (int n = 0; n < 2; ++n) _Pragma("unroll") for (int k = 0; k < 2; ++k) dst[n][k] = *(const PG_LAS bf16x8*)(lds + PG_SB(b, h) + boff + n * 2048 + k * 1024); } while (0)
; #define PG_MMA(ai, bj, At, Bt) do { __builtin_amdgcn_s_setprio(1); _Pragma("unroll") for (int m = 0; m < 4; ++m) _Pragma("unroll") for (int n = 0; n < 2; ++n) _Pragma("unroll") for (int k = 0; k < 2; ++k) \
;     acc[ai][bj][m][n] = __builtin_amdgcn_mfma_f32_16x16x32_bf16(Bt[n][k], At[m][k], acc[ai][bj][m][n], 0, 0, 0); __builtin_amdgcn_s_setprio(0); } while (0)
; #define PG_WAIT_V(n) asm volatile("s_waitcnt vmcnt(" #n ")" ::: "memory")
; #define PG_WAIT_L(n) asm volatile("s_waitcnt lgkmcnt(" #n ")" ::: "memory")
; #define PG_BAR __builtin_amdgcn_s_barrier()
; #define PG_SCHED __builtin_amdgcn_sched_barrier(0)
; template <class Epi>
; DEV void pg_gemm_phase(PG_LAS unsigned char* lds, const u16* gA, const u16* gBt, int M, int N, int K, const PgOrder& S, const Epi& E) {
;     ...
;     for (int t = 0; t < nt; t += 2) {
;       const bool last = (t == nt - 2);
;       const char* a1 = cA + (size_t)(t + 1) * kstep;
;       const char* a2 = last ? nA : cA + (size_t)(t + 2) * kstep; const char* b2 = last ? nB : cB + (size_t)(t + 2) * kstep;
;       const char* a3 = a2 + kstep; const char* b3 = b2 + kstep;
;       PG_LDB(B0, 0, 0); PG_SCHED; PG_LDA(At, 0, 0); PG_STAGE(PG_SA(1, 1), a1 + hstepA, voffA);
;       PG_WAIT_L(8); PG_BAR; PG_WAIT_L(0); PG_MMA(0, 0, At, B0); PG_BAR; PG_SCHED;
;       PG_LDB(B1, 0, 1); PG_STAGE(PG_SB(0, 0), b2, voffB);
;       PG_BAR; PG_WAIT_L(0); PG_MMA(0, 1, At, B1); PG_BAR;
;       PG_LDA(At, 0, 1); PG_STAGE(PG_SA(0, 0), a2, voffA);
;       PG_BAR; PG_WAIT_L(0); PG_MMA(1, 0, At, B0); PG_BAR; PG_SCHED;
;       PG_STAGE(PG_SB(0, 1), b2 + hstepB, voffB);
;       PG_WAIT_V(6); PG_BAR; PG_MMA(1, 1, At, B1); PG_BAR;
.LBB0_102:
	s_add_u32 s8, s2, 0xfffc0080
	s_addc_u32 s9, s3, -1
	s_add_i32 s79, 0, 0x10000
	s_waitcnt vmcnt(6)
	v_add_u32_e32 v28, s79, v169
	ds_read_b128 v[16:19], v28
	ds_read_b128 v[20:23], v28 offset:1024
	ds_read_b128 v[24:27], v28 offset:2048
	ds_read_b128 v[28:31], v28 offset:3072
	s_cmp_eq_u32 s78, 12
	s_cselect_b32 s15, s13, s9
	s_cselect_b32 s14, s22, s8
	s_cselect_b32 s9, s34, s75
	s_cselect_b32 s8, s35, s71
	v_lshl_add_u64 v[166:167], s[2:3], 0, v[164:165]
	s_add_i32 m0, s55, 0xc000
	ds_read_b128 v[172:175], v171
	ds_read_b128 v[176:179], v171 offset:1024
	ds_read_b128 v[180:183], v171 offset:2048
	ds_read_b128 v[194:197], v171 offset:3072
	ds_read_b128 v[198:201], v171 offset:4096
	ds_read_b128 v[202:205], v171 offset:5120
	ds_read_b128 v[206:209], v171 offset:6144
	ds_read_b128 v[210:213], v171 offset:7168
	global_load_lds_dwordx4 v[166:167], off
	v_lshl_add_u64 v[166:167], s[2:3], 0, v[162:163]
	s_add_i32 m0, s55, 0xe000
	s_nop 0
	global_load_lds_dwordx4 v[166:167], off
	s_waitcnt lgkmcnt(8)
	s_barrier
	s_waitcnt lgkmcnt(0)
	s_setprio 1
	s_waitcnt lgkmcnt(0)
	v_mfma_f32_16x16x32_bf16 v[140:143], v[16:19], v[172:175], v[140:143]
	v_mfma_f32_16x16x32_bf16 v[136:139], v[24:27], v[172:175], v[136:139]
	v_mfma_f32_16x16x32_bf16 v[124:127], v[16:19], v[180:183], v[124:127]
	v_mfma_f32_16x16x32_bf16 v[120:123], v[24:27], v[180:183], v[120:123]
	v_mfma_f32_16x16x32_bf16 v[108:111], v[16:19], v[198:201], v[108:111]
	v_mfma_f32_16x16x32_bf16 v[104:107], v[24:27], v[198:201], v[104:107]
	v_mfma_f32_16x16x32_bf16 v[92:95], v[16:19], v[206:209], v[92:95]
	v_mfma_f32_16x16x32_bf16 v[88:91], v[24:27], v[206:209], v[88:91]
	v_mfma_f32_16x16x32_bf16 v[140:143], v[20:23], v[176:179], v[140:143]
	v_mfma_f32_16x16x32_bf16 v[136:139], v[28:31], v[176:179], v[136:139]
	v_mfma_f32_16x16x32_bf16 v[124:127], v[20:23], v[194:197], v[124:127]
	v_mfma_f32_16x16x32_bf16 v[120:123], v[28:31], v[194:197], v[120:123]
	v_mfma_f32_16x16x32_bf16 v[108:111], v[20:23], v[202:205], v[108:111]
	v_mfma_f32_16x16x32_bf16 v[104:107], v[28:31], v[202:205], v[104:107]
	v_mfma_f32_16x16x32_bf16 v[92:95], v[20:23], v[210:213], v[92:95]
	v_mfma_f32_16x16x32_bf16 v[88:91], v[28:31], v[210:213], v[88:91]
	s_setprio 0
	s_barrier
	s_add_i32 vcc_lo, 0, 0x14000
	v_add_u32_e32 v166, vcc_lo, v169
	s_add_i32 s79, s79, s54
	ds_read_b128 v[214:217], v166
	ds_read_b128 v[218:221], v166 offset:1024
	ds_read_b128 v[222:225], v166 offset:2048
	ds_read_b128 v[232:235], v166 offset:3072
	v_lshl_add_u64 v[166:167], s[8:9], 0, v[146:147]
	s_mov_b32 m0, s79
	v_lshl_add_u64 v[186:187], s[8:9], 0, v[150:151]
	global_load_lds_dwordx4 v[166:167], off
	s_add_i32 m0, s79, 0x2000
	s_nop 0
	global_load_lds_dwordx4 v[186:187], off
	s_barrier
	s_waitcnt lgkmcnt(0)
	s_setprio 1
	s_waitcnt lgkmcnt(0)
	v_mfma_f32_16x16x32_bf16 v[132:135], v[214:217], v[172:175], v[132:135]
	v_mfma_f32_16x16x32_bf16 v[128:131], v[222:225], v[172:175], v[128:131]
	v_mfma_f32_16x16x32_bf16 v[116:119], v[214:217], v[180:183], v[116:119]
	v_mfma_f32_16x16x32_bf16 v[112:115], v[222:225], v[180:183], v[112:115]
	v_mfma_f32_16x16x32_bf16 v[100:103], v[214:217], v[198:201], v[100:103]
	v_mfma_f32_16x16x32_bf16 v[96:99], v[222:225], v[198:201], v[96:99]
	v_mfma_f32_16x16x32_bf16 v[84:87], v[214:217], v[206:209], v[84:87]
	v_mfma_f32_16x16x32_bf16 v[80:83], v[222:225], v[206:209], v[80:83]
	v_mfma_f32_16x16x32_bf16 v[132:135], v[218:221], v[176:179], v[132:135]
	v_mfma_f32_16x16x32_bf16 v[128:131], v[232:235], v[176:179], v[128:131]
	v_mfma_f32_16x16x32_bf16 v[116:119], v[218:221], v[194:197], v[116:119]
	v_mfma_f32_16x16x32_bf16 v[112:115], v[232:235], v[194:197], v[112:115]
	v_mfma_f32_16x16x32_bf16 v[100:103], v[218:221], v[202:205], v[100:103]
	v_mfma_f32_16x16x32_bf16 v[96:99], v[232:235], v[202:205], v[96:99]
	v_mfma_f32_16x16x32_bf16 v[84:87], v[218:221], v[210:213], v[84:87]
	v_mfma_f32_16x16x32_bf16 v[80:83], v[232:235], v[210:213], v[80:83]
	s_setprio 0
	s_mov_b32 m0, s55
	v_lshl_add_u64 v[188:189], s[14:15], 0, v[144:145]
	s_barrier
	ds_read_b128 v[172:175], v171 offset:16384
	ds_read_b128 v[176:179], v171 offset:17408
	ds_read_b128 v[180:183], v171 offset:18432
	ds_read_b128 v[194:197], v171 offset:19456
	ds_read_b128 v[198:201], v171 offset:20480
	ds_read_b128 v[202:205], v171 offset:21504
	ds_read_b128 v[206:209], v171 offset:22528
	ds_read_b128 v[210:213], v171 offset:23552
	global_load_lds_dwordx4 v[188:189], off
	v_lshl_add_u64 v[236:237], s[14:15], 0, v[148:149]
	s_mov_b32 m0, s60
	s_nop 0
	global_load_lds_dwordx4 v[236:237], off
	s_barrier
	s_waitcnt lgkmcnt(0)
	s_setprio 1
	s_waitcnt lgkmcnt(0)
	v_mfma_f32_16x16x32_bf16 v[76:79], v[16:19], v[172:175], v[76:79]
	v_mfma_f32_16x16x32_bf16 v[72:75], v[24:27], v[172:175], v[72:75]
	v_mfma_f32_16x16x32_bf16 v[60:63], v[16:19], v[180:183], v[60:63]
	v_mfma_f32_16x16x32_bf16 v[56:59], v[24:27], v[180:183], v[56:59]
	v_mfma_f32_16x16x32_bf16 v[44:47], v[16:19], v[198:201], v[44:47]
	v_mfma_f32_16x16x32_bf16 v[40:43], v[24:27], v[198:201], v[40:43]
	v_mfma_f32_16x16x32_bf16 v[12:15], v[16:19], v[206:209], v[12:15]
	v_mfma_f32_16x16x32_bf16 v[8:11], v[24:27], v[206:209], v[8:11]
	v_mfma_f32_16x16x32_bf16 v[76:79], v[20:23], v[176:179], v[76:79]
	v_mfma_f32_16x16x32_bf16 v[72:75], v[28:31], v[176:179], v[72:75]
	v_mfma_f32_16x16x32_bf16 v[60:63], v[20:23], v[194:197], v[60:63]
	v_mfma_f32_16x16x32_bf16 v[56:59], v[28:31], v[194:197], v[56:59]
	v_mfma_f32_16x16x32_bf16 v[44:47], v[20:23], v[202:205], v[44:47]
	v_mfma_f32_16x16x32_bf16 v[40:43], v[28:31], v[202:205], v[40:43]
	v_mfma_f32_16x16x32_bf16 v[12:15], v[20:23], v[210:213], v[12:15]
	v_mfma_f32_16x16x32_bf16 v[8:11], v[28:31], v[210:213], v[8:11]
	s_setprio 0
	s_barrier
	s_add_u32 s82, s8, 0x10000
	s_addc_u32 s83, s9, 0
	s_add_i32 s79, vcc_lo, s54
	v_lshl_add_u64 v[16:17], s[82:83], 0, v[146:147]
	s_mov_b32 m0, s79
	s_nop 0
	global_load_lds_dwordx4 v[16:17], off
	v_lshl_add_u64 v[16:17], s[82:83], 0, v[150:151]
	s_add_i32 m0, s79, 0x2000
	s_nop 0
	global_load_lds_dwordx4 v[16:17], off
	s_waitcnt vmcnt(6)
	s_barrier
	s_setprio 1
	v_mfma_f32_16x16x32_bf16 v[36:39], v[214:217], v[198:201], v[36:39]
	v_mfma_f32_16x16x32_bf16 v[32:35], v[222:225], v[198:201], v[32:35]
	v_mfma_f32_16x16x32_bf16 v[4:7], v[214:217], v[206:209], v[4:7]
	v_mfma_f32_16x16x32_bf16 v[0:3], v[222:225], v[206:209], v[0:3]
	v_mfma_f32_16x16x32_bf16 v[16:19], v[214:217], v[172:175], v[68:71]
	v_mfma_f32_16x16x32_bf16 v[20:23], v[222:225], v[172:175], v[64:67]
	v_mfma_f32_16x16x32_bf16 v[24:27], v[214:217], v[180:183], v[52:55]
	v_mfma_f32_16x16x32_bf16 v[28:31], v[222:225], v[180:183], v[48:51]
	v_mfma_f32_16x16x32_bf16 v[36:39], v[218:221], v[202:205], v[36:39]
	v_mfma_f32_16x16x32_bf16 v[32:35], v[232:235], v[202:205], v[32:35]
	v_mfma_f32_16x16x32_bf16 v[4:7], v[218:221], v[210:213], v[4:7]
	v_mfma_f32_16x16x32_bf16 v[0:3], v[232:235], v[210:213], v[0:3]
	v_mfma_f32_16x16x32_bf16 v[16:19], v[218:221], v[176:179], v[16:19]
	v_mfma_f32_16x16x32_bf16 v[20:23], v[232:235], v[176:179], v[20:23]
	v_mfma_f32_16x16x32_bf16 v[24:27], v[218:221], v[194:197], v[24:27]
	v_mfma_f32_16x16x32_bf16 v[28:31], v[232:235], v[194:197], v[28:31]
	s_setprio 0
	s_add_i32 s79, 0, 0x18000
	v_add_u32_e32 v68, s79, v169
	s_barrier
	ds_read_b128 v[48:51], v68
	ds_read_b128 v[52:55], v68 offset:1024
	ds_read_b128 v[64:67], v68 offset:2048
	ds_read_b128 v[68:71], v68 offset:3072
	s_add_u32 s14, s14, 0x40000
	s_addc_u32 s15, s15, 0
	s_mov_b32 m0, s61
	v_lshl_add_u64 v[214:215], s[14:15], 0, v[144:145]
	ds_read_b128 v[172:175], v171 offset:32768
	ds_read_b128 v[176:179], v171 offset:33792
	ds_read_b128 v[180:183], v171 offset:34816
	ds_read_b128 v[194:197], v171 offset:35840
	ds_read_b128 v[198:201], v171 offset:36864
	ds_read_b128 v[202:205], v171 offset:37888
	ds_read_b128 v[206:209], v171 offset:38912
	ds_read_b128 v[210:213], v171 offset:39936
	global_load_lds_dwordx4 v[214:215], off
	v_lshl_add_u64 v[214:215], s[14:15], 0, v[148:149]
	s_mov_b32 m0, s62
	s_nop 0
	global_load_lds_dwordx4 v[214:215], off
	s_waitcnt lgkmcnt(8)
	s_barrier
	s_waitcnt lgkmcnt(0)
	s_setprio 1
	s_waitcnt lgkmcnt(0)
	v_mfma_f32_16x16x32_bf16 v[140:143], v[48:51], v[172:175], v[140:143]
	v_mfma_f32_16x16x32_bf16 v[136:139], v[64:67], v[172:175], v[136:139]
	v_mfma_f32_16x16x32_bf16 v[124:127], v[48:51], v[180:183], v[124:127]
	v_mfma_f32_16x16x32_bf16 v[120:123], v[64:67], v[180:183], v[120:123]
	v_mfma_f32_16x16x32_bf16 v[108:111], v[48:51], v[198:201], v[108:111]
	v_mfma_f32_16x16x32_bf16 v[104:107], v[64:67], v[198:201], v[104:107]
	v_mfma_f32_16x16x32_bf16 v[92:95], v[48:51], v[206:209], v[92:95]
	v_mfma_f32_16x16x32_bf16 v[88:91], v[64:67], v[206:209], v[88:91]
	v_mfma_f32_16x16x32_bf16 v[140:143], v[52:55], v[176:179], v[140:143]
	v_mfma_f32_16x16x32_bf16 v[136:139], v[68:71], v[176:179], v[136:139]
	v_mfma_f32_16x16x32_bf16 v[124:127], v[52:55], v[194:197], v[124:127]
	v_mfma_f32_16x16x32_bf16 v[120:123], v[68:71], v[194:197], v[120:123]
	v_mfma_f32_16x16x32_bf16 v[108:111], v[52:55], v[202:205], v[108:111]
	v_mfma_f32_16x16x32_bf16 v[104:107], v[68:71], v[202:205], v[104:107]
	v_mfma_f32_16x16x32_bf16 v[92:95], v[52:55], v[210:213], v[92:95]
	v_mfma_f32_16x16x32_bf16 v[88:91], v[68:71], v[210:213], v[88:91]
	s_setprio 0
	s_barrier
	s_add_i32 s14, 0, 0x1c000
	s_add_i32 s15, s79, s54
	v_add_u32_e32 v168, s14, v169
	v_lshl_add_u64 v[166:167], v[166:167], 0, s[30:31]
	s_mov_b32 m0, s15
	ds_read_b128 v[214:217], v168
	ds_read_b128 v[218:221], v168 offset:1024
	ds_read_b128 v[222:225], v168 offset:2048
	ds_read_b128 v[232:235], v168 offset:3072
	global_load_lds_dwordx4 v[166:167], off
	v_lshl_add_u64 v[166:167], v[186:187], 0, s[30:31]
	s_add_i32 m0, s15, 0x2000
	s_nop 0
	global_load_lds_dwordx4 v[166:167], off
	s_barrier
	s_waitcnt lgkmcnt(0)
	s_setprio 1
	s_waitcnt lgkmcnt(0)
	v_mfma_f32_16x16x32_bf16 v[132:135], v[214:217], v[172:175], v[132:135]
	v_mfma_f32_16x16x32_bf16 v[128:131], v[222:225], v[172:175], v[128:131]
	v_mfma_f32_16x16x32_bf16 v[116:119], v[214:217], v[180:183], v[116:119]
	v_mfma_f32_16x16x32_bf16 v[112:115], v[222:225], v[180:183], v[112:115]
	v_mfma_f32_16x16x32_bf16 v[100:103], v[214:217], v[198:201], v[100:103]
	v_mfma_f32_16x16x32_bf16 v[96:99], v[222:225], v[198:201], v[96:99]
	v_mfma_f32_16x16x32_bf16 v[84:87], v[214:217], v[206:209], v[84:87]
	v_mfma_f32_16x16x32_bf16 v[80:83], v[222:225], v[206:209], v[80:83]
	v_mfma_f32_16x16x32_bf16 v[132:135], v[218:221], v[176:179], v[132:135]
	v_mfma_f32_16x16x32_bf16 v[128:131], v[232:235], v[176:179], v[128:131]
	v_mfma_f32_16x16x32_bf16 v[116:119], v[218:221], v[194:197], v[116:119]
	v_mfma_f32_16x16x32_bf16 v[112:115], v[232:235], v[194:197], v[112:115]
	v_mfma_f32_16x16x32_bf16 v[100:103], v[218:221], v[202:205], v[100:103]
	v_mfma_f32_16x16x32_bf16 v[96:99], v[232:235], v[202:205], v[96:99]
	v_mfma_f32_16x16x32_bf16 v[84:87], v[218:221], v[210:213], v[84:87]
	v_mfma_f32_16x16x32_bf16 v[80:83], v[232:235], v[210:213], v[80:83]
	s_setprio 0
	s_mov_b32 m0, s63
	v_lshl_add_u64 v[166:167], v[188:189], 0, s[30:31]
	s_barrier
	ds_read_b128 v[172:175], v171 offset:49152
	ds_read_b128 v[176:179], v171 offset:50176
	ds_read_b128 v[180:183], v171 offset:51200
	ds_read_b128 v[194:197], v171 offset:52224
	ds_read_b128 v[198:201], v171 offset:53248
	ds_read_b128 v[202:205], v171 offset:54272
	ds_read_b128 v[206:209], v171 offset:55296
	ds_read_b128 v[210:213], v171 offset:56320
	global_load_lds_dwordx4 v[166:167], off
	v_lshl_add_u64 v[166:167], v[236:237], 0, s[30:31]
	s_mov_b32 m0, s64
	s_nop 0
	global_load_lds_dwordx4 v[166:167], off
	s_barrier
	s_waitcnt lgkmcnt(0)
	s_setprio 1
	s_waitcnt lgkmcnt(0)
	v_mfma_f32_16x16x32_bf16 v[76:79], v[48:51], v[172:175], v[76:79]
	v_mfma_f32_16x16x32_bf16 v[72:75], v[64:67], v[172:175], v[72:75]
	v_mfma_f32_16x16x32_bf16 v[60:63], v[48:51], v[180:183], v[60:63]
	v_mfma_f32_16x16x32_bf16 v[56:59], v[64:67], v[180:183], v[56:59]
	v_mfma_f32_16x16x32_bf16 v[44:47], v[48:51], v[198:201], v[44:47]
	v_mfma_f32_16x16x32_bf16 v[40:43], v[64:67], v[198:201], v[40:43]
	v_mfma_f32_16x16x32_bf16 v[12:15], v[48:51], v[206:209], v[12:15]
	v_mfma_f32_16x16x32_bf16 v[8:11], v[64:67], v[206:209], v[8:11]
	v_mfma_f32_16x16x32_bf16 v[76:79], v[52:55], v[176:179], v[76:79]
	v_mfma_f32_16x16x32_bf16 v[72:75], v[68:71], v[176:179], v[72:75]
	v_mfma_f32_16x16x32_bf16 v[60:63], v[52:55], v[194:197], v[60:63]
	v_mfma_f32_16x16x32_bf16 v[56:59], v[68:71], v[194:197], v[56:59]
	v_mfma_f32_16x16x32_bf16 v[44:47], v[52:55], v[202:205], v[44:47]
	v_mfma_f32_16x16x32_bf16 v[40:43], v[68:71], v[202:205], v[40:43]
	v_mfma_f32_16x16x32_bf16 v[12:15], v[52:55], v[210:213], v[12:15]
	v_mfma_f32_16x16x32_bf16 v[8:11], v[68:71], v[210:213], v[8:11]
	s_setprio 0
	s_barrier
	s_add_u32 s8, s8, 0x10080
	s_addc_u32 s9, s9, 0
	s_add_i32 s14, s14, s54
	v_lshl_add_u64 v[48:49], s[8:9], 0, v[146:147]
	s_mov_b32 m0, s14
	s_nop 0
	global_load_lds_dwordx4 v[48:49], off
	v_lshl_add_u64 v[48:49], s[8:9], 0, v[150:151]
	s_add_i32 m0, s14, 0x2000
	s_nop 0
	global_load_lds_dwordx4 v[48:49], off
	s_waitcnt vmcnt(6)
	s_barrier
	s_setprio 1
	v_mfma_f32_16x16x32_bf16 v[16:19], v[214:217], v[172:175], v[16:19]
	v_mfma_f32_16x16x32_bf16 v[68:71], v[218:221], v[176:179], v[16:19]
	v_mfma_f32_16x16x32_bf16 v[16:19], v[222:225], v[172:175], v[20:23]
	v_mfma_f32_16x16x32_bf16 v[64:67], v[232:235], v[176:179], v[16:19]
	v_mfma_f32_16x16x32_bf16 v[16:19], v[214:217], v[180:183], v[24:27]
	v_mfma_f32_16x16x32_bf16 v[52:55], v[218:221], v[194:197], v[16:19]
	v_mfma_f32_16x16x32_bf16 v[16:19], v[222:225], v[180:183], v[28:31]
	v_mfma_f32_16x16x32_bf16 v[48:51], v[232:235], v[194:197], v[16:19]
	v_mfma_f32_16x16x32_bf16 v[16:19], v[214:217], v[198:201], v[36:39]
	v_mfma_f32_16x16x32_bf16 v[36:39], v[218:221], v[202:205], v[16:19]
	v_mfma_f32_16x16x32_bf16 v[16:19], v[222:225], v[198:201], v[32:35]
	v_mfma_f32_16x16x32_bf16 v[4:7], v[214:217], v[206:209], v[4:7]
	v_mfma_f32_16x16x32_bf16 v[0:3], v[222:225], v[206:209], v[0:3]
	v_mfma_f32_16x16x32_bf16 v[32:35], v[232:235], v[202:205], v[16:19]
	v_mfma_f32_16x16x32_bf16 v[4:7], v[218:221], v[210:213], v[4:7]
	v_mfma_f32_16x16x32_bf16 v[0:3], v[232:235], v[210:213], v[0:3]
	s_setprio 0
	s_add_i32 s78, s78, 2
	s_add_u32 s71, s71, 0x100
	s_addc_u32 s75, s75, 0
	s_add_u32 s2, s2, 0x100
	s_addc_u32 s3, s3, 0
	s_cmp_gt_u32 s78, 13
	s_barrier
	s_cbranch_scc0 .LBB0_102
	s_cmp_lt_i32 s10, 2
	s_cselect_b64 s[8:9], -1, 0
	s_cmp_gt_i32 s10, 3
	s_cselect_b64 s[2:3], -1, 0
	s_and_b64 vcc, exec, s[2:3]
	s_cbranch_vccnz .LBB0_105
	s_and_b64 s[14:15], s[8:9], exec
	s_movk_i32 s13, 0x200
	s_cselect_b32 s22, 0x100, s13
	v_lshl_add_u64 v[16:17], v[154:155], 0, s[22:23]
	s_waitcnt vmcnt(0)
	flat_load_dwordx4 v[28:31], v[16:17]
	flat_load_dwordx4 v[24:27], v[16:17] offset:16
	flat_load_dwordx4 v[20:23], v[16:17] offset:128
	s_nop 0
	flat_load_dwordx4 v[16:19], v[16:17] offset:144
